# outproj K-loop on v_mfma_f32_16x16x32_bf16 (4x4 blocks per wave, 16 fragment reads per step, barrier skewed before the last 8 MFMAs, DMA woven into the first 16); gates and row-staged epilogue re-deri
# baseline (speedup 1.0000x reference)
; DI void phase_outproj(const Params& p, int l, char* smem, int tid) {
;   const int lane = tid & 63, w = tid >> 6, r = lane & 31, h = lane >> 5, wm = w >> 1, wn = w & 1;
;   GemmLds* s = (GemmLds*)smem;
;   const u16* ACC = p.Pk;
;   const bool dyn = (l == 0);
;   unsigned* qc = p.bar + 4096 + 384;
;   for (int it = (dyn ? fetch_item(qc, smem) : (int)blockIdx.x); it < 272 * 8; it = (dyn ? fetch_item(qc, smem) : it + (int)gridDim.x)) {
;     const int mt = it >> 3, nt = it & 7, m0 = mt * 128, n0 = nt * 128;
;     if (l == 1 && (mt % 34) < 2) continue;
;     f32x16 acc[2][2]; zero_acc<2>(acc);
;     gemm_main<2>(ACC + (size_t)m0 * 1024, 1024, p.WtOut + (size_t)l * 1024 * 1024 + (size_t)n0 * 1024, 1024, 1024, acc, s, tid);
.LBB0_1221:
	s_or_b64 exec, exec, s[4:5]
	v_mov_b32_e32 v0, v206
	s_and_b64 vcc, exec, s[0:1]
	v_mov_b32_e32 v146, s48
	s_waitcnt lgkmcnt(0)
	s_barrier
	v_readlane_b32 s18, v254, 19
	v_and_b32_e32 v138, 63, v206
	v_lshrrev_b32_e32 v139, 6, v206
	v_lshrrev_b32_e32 v140, 3, v138
	v_lshl_add_u32 v140, v139, 5, v140
	v_lshlrev_b32_e32 v140, 11, v140
	v_and_b32_e32 v141, 7, v138
	v_lshrrev_b32_e32 v138, 4, v138
	v_xor_b32_e32 v141, v141, v138
	v_lshl_or_b32 v130, v141, 4, v140
	v_xor_b32_e32 v131, 64, v130
	v_add_u32_e32 v131, 16384, v131
	v_add_u32_e32 v132, 32768, v130
	v_add_u32_e32 v133, 32768, v131
	v_lshrrev_b32_e32 v156, 6, v206
	v_and_b32_e32 v138, 15, v206
	v_bfe_u32 v139, v206, 4, 2
	v_bfe_u32 v140, v138, 1, 3
	v_xor_b32_e32 v140, v140, v139
	v_lshlrev_b32_e32 v140, 4, v140
	v_lshl_or_b32 v140, v138, 7, v140
	v_lshrrev_b32_e32 v141, 7, v206
	v_lshl_add_u32 v134, v141, 13, v140
	v_bfe_u32 v141, v206, 6, 1
	v_lshl_add_u32 v136, v141, 13, v140
	v_add_u32_e32 v136, 0x4000, v136
	v_xor_b32_e32 v135, 64, v134
	v_xor_b32_e32 v137, 64, v136
	v_lshlrev_b32_e32 v167, 8, v141
	v_lshl_or_b32 v167, v139, 4, v167
	v_lshrrev_b32_e32 v138, 6, v206
	v_mul_u32_u24_e32 v138, 0x2400, v138
	v_and_b32_e32 v139, 31, v206
	v_mul_u32_u24_e32 v139, 0x90, v139
	v_bfe_u32 v140, v206, 5, 1
	v_lshl_add_u32 v139, v140, 3, v139
	v_add_u32_e32 v164, v138, v139
	v_bfe_u32 v139, v206, 3, 3
	v_mul_u32_u24_e32 v139, 0x90, v139
	v_and_b32_e32 v140, 7, v206
	v_lshl_add_u32 v139, v140, 4, v139
	v_add_u32_e32 v165, v138, v139
	v_lshrrev_b32_e32 v138, 6, v206
	v_mul_u32_u24_e32 v138, 0x2400, v138
	v_and_b32_e32 v139, 15, v206
	v_mul_u32_u24_e32 v139, 0x90, v139
	v_bfe_u32 v140, v206, 4, 2
	v_lshl_add_u32 v139, v140, 3, v139
	v_add_u32_e32 v164, v138, v139
	v_bfe_u32 v138, v206, 3, 3
	v_lshrrev_b32_e32 v139, 7, v206
	v_lshl_add_u32 v138, v139, 6, v138
	v_mul_u32_u24_e32 v138, 0x800, v138
	v_bfe_u32 v139, v206, 6, 1
	v_lshlrev_b32_e32 v139, 7, v139
	v_and_b32_e32 v140, 7, v206
	v_lshl_or_b32 v139, v140, 4, v139
	v_add_u32_e32 v166, v138, v139
	v_readfirstlane_b32 s10, v156
	s_lshl_b32 s10, s10, 12
	s_lshl_b32 s6, s18, 21
	s_add_u32 s14, s96, 0x1cc00000
	s_addc_u32 s15, s97, 0
	s_add_u32 s14, s14, s6
	s_addc_u32 s15, s15, 0
	s_mov_b32 s12, s48
.Lop_item:
	s_cmp_eq_u32 s18, 0
	s_cbranch_scc0 .Lop_static
	s_barrier
	s_cmp_eq_u32 s10, 0
	s_cbranch_scc0 .Lop_fetch_wait
	s_mov_b64 s[6:7], exec
	s_mov_b64 exec, 1
	s_add_u32 s8, s96, 0x1da5d600
	s_addc_u32 s9, s97, 0
	v_mov_b32_e32 v138, 1
	v_mov_b32_e32 v139, 0
	global_atomic_add v140, v139, v138, s[8:9] sc0
	v_mov_b32_e32 v141, 0x125f0
	s_waitcnt vmcnt(0)
	ds_write_b32 v141, v140
	s_waitcnt lgkmcnt(0)
	s_mov_b64 exec, s[6:7]
.Lop_fetch_wait:
	s_barrier
	v_mov_b32_e32 v141, 0x125f0
	ds_read_b32 v140, v141
	s_waitcnt lgkmcnt(0)
	v_readfirstlane_b32 s12, v140
	s_cmpk_lt_u32 s12, 0x880
	s_cbranch_scc0 .Lop_done
	s_lshr_b32 s20, s12, 3
	s_mul_hi_u32 s6, s20, 0x78787879
	s_lshr_b32 s6, s6, 4
	s_mul_i32 s7, s6, 34
	s_sub_u32 s7, s20, s7
	s_cmp_lt_u32 s7, 2
	s_cselect_b32 s21, 8, s6
	s_branch .Lop_decoded

; #define G_STORE(S, bf) { *(uint4*)&s->a[bf][srow][skc] = S##a0; *(uint4*)&s->a[bf][srow + 32][skc] = S##a1; \
;     if (MB == 2) { *(uint4*)&s->a[bf][srow + 64][skc] = S##a2; *(uint4*)&s->a[bf][srow + 96][skc] = S##a3; } \
;     *(uint4*)&s->b[bf][srow][skc] = S##b0; *(uint4*)&s->b[bf][srow + 32][skc] = S##b1; *(uint4*)&s->b[bf][srow + 64][skc] = S##b2; *(uint4*)&s->b[bf][srow + 96][skc] = S##b3; }
; template <int MB, bool PF2 = true>
; DI void gemm_main(const u16* __restrict__ A, int lda, const u16* __restrict__ B, int ldb, int K, f32x16 (&acc)[MB][2], GemmLds* s, int tid) {
;     ...
;   G_LOAD(p, 64);
;   __syncthreads();
;   for (int kt = 0; kt < KT; kt += 2) {
;     { const int k2 = min((kt + 2) * 64, klast); G_LOAD(q, k2); }
;     __builtin_amdgcn_sched_barrier(0);
;     G_COMPUTE(0);
;     G_STORE(p, 1);
; DI void phase_outproj(const Params& p, int l, char* smem, int tid) {
;     ...
;     f32x16 acc[2][2]; zero_acc<2>(acc);
;     gemm_main<2>(ACC + (size_t)m0 * 1024, 1024, p.WtOut + (size_t)l * 1024 * 1024 + (size_t)n0 * 1024, 1024, 1024, acc, s, tid);
;     u16* O = p.G;
; #pragma unroll
;     for (int mb = 0; mb < 2; mb++)
; #pragma unroll
;       for (int nb = 0; nb < 2; nb++) {
;         const int rowb = m0 + wm * 64 + mb * 32, col = n0 + wn * 64 + nb * 32 + r;
;         const int b = rowb / SEQA, pos0 = rowb % SEQA;
;         const float gate = p.mod[((size_t)l * 9 + ((pos0 < CTXL) ? 8 : b)) * 3072 + 2048 + col];
.Lop_decoded:
	s_and_b32 s13, s12, 7
	s_mul_i32 s7, s18, 9
	s_add_u32 s7, s7, s21
	s_mul_i32 s7, s7, 0x3000
	s_lshl_b32 s6, s13, 9
	s_add_u32 s7, s7, s6
	s_add_u32 s7, s7, 0x1d002000
	s_add_u32 s6, s96, s7
	s_addc_u32 s7, s97, 0
	global_load_dwordx4 v[168:171], v167, s[6:7] offset:0
	global_load_dwordx4 v[172:175], v167, s[6:7] offset:64
	global_load_dwordx4 v[176:179], v167, s[6:7] offset:128
	global_load_dwordx4 v[180:183], v167, s[6:7] offset:192
	s_lshl_b32 s2, s20, 18
	s_add_u32 s4, s90, s2
	s_addc_u32 s5, s91, 0
	s_lshl_b32 s3, s13, 18
	s_add_u32 s8, s14, s3
	s_addc_u32 s9, s15, 0
	s_lshl_b32 s3, s13, 8
	s_add_u32 s2, s2, s3
	s_add_u32 s2, s2, 0x16720000
	s_add_u32 s16, s96, s2
	s_addc_u32 s17, s97, 0
	v_mov_b32_e32 v2, 0
	v_mov_b32_e32 v3, 0
	v_mov_b32_e32 v4, 0
	v_mov_b32_e32 v5, 0
	v_mov_b32_e32 v6, 0
	v_mov_b32_e32 v7, 0
	v_mov_b32_e32 v8, 0
	v_mov_b32_e32 v9, 0
	v_mov_b32_e32 v10, 0
	v_mov_b32_e32 v11, 0
	v_mov_b32_e32 v12, 0
	v_mov_b32_e32 v13, 0
	v_mov_b32_e32 v14, 0
	v_mov_b32_e32 v15, 0
	v_mov_b32_e32 v16, 0
	v_mov_b32_e32 v17, 0
	v_mov_b32_e32 v18, 0
	v_mov_b32_e32 v19, 0
	v_mov_b32_e32 v20, 0
	v_mov_b32_e32 v21, 0
	v_mov_b32_e32 v22, 0
	v_mov_b32_e32 v23, 0
	v_mov_b32_e32 v24, 0
	v_mov_b32_e32 v25, 0
	v_mov_b32_e32 v26, 0
	v_mov_b32_e32 v27, 0
	v_mov_b32_e32 v28, 0
	v_mov_b32_e32 v29, 0
	v_mov_b32_e32 v30, 0
	v_mov_b32_e32 v31, 0
	v_mov_b32_e32 v32, 0
	v_mov_b32_e32 v33, 0
	v_mov_b32_e32 v34, 0
	v_mov_b32_e32 v35, 0
	v_mov_b32_e32 v36, 0
	v_mov_b32_e32 v37, 0
	v_mov_b32_e32 v38, 0
	v_mov_b32_e32 v39, 0
	v_mov_b32_e32 v40, 0
	v_mov_b32_e32 v41, 0
	v_mov_b32_e32 v42, 0
	v_mov_b32_e32 v43, 0
	v_mov_b32_e32 v44, 0
	v_mov_b32_e32 v45, 0
	v_mov_b32_e32 v46, 0
	v_mov_b32_e32 v47, 0
	v_mov_b32_e32 v48, 0
	v_mov_b32_e32 v49, 0
	v_mov_b32_e32 v50, 0
	v_mov_b32_e32 v51, 0
	v_mov_b32_e32 v52, 0
	v_mov_b32_e32 v53, 0
	v_mov_b32_e32 v54, 0
	v_mov_b32_e32 v55, 0
	v_mov_b32_e32 v56, 0
	v_mov_b32_e32 v57, 0
	v_mov_b32_e32 v58, 0
	v_mov_b32_e32 v59, 0
	v_mov_b32_e32 v60, 0
	v_mov_b32_e32 v61, 0
	v_mov_b32_e32 v62, 0
	v_mov_b32_e32 v63, 0
	v_mov_b32_e32 v64, 0
	v_mov_b32_e32 v65, 0
	s_add_u32 m0, s10, 0x0
	s_nop 0
	global_load_lds_dwordx4 v130, s[4:5]
	s_add_u32 m0, s10, 0x400
	s_nop 0
	global_load_lds_dwordx4 v131, s[4:5]
	s_add_u32 m0, s10, 0x800
	s_nop 0
	global_load_lds_dwordx4 v132, s[4:5]
	s_add_u32 m0, s10, 0xc00
	s_nop 0
	global_load_lds_dwordx4 v133, s[4:5]
	s_add_u32 s4, s4, 128
	s_addc_u32 s5, s5, 0
	s_add_u32 m0, s10, 0x4000
	s_nop 0
	global_load_lds_dwordx4 v130, s[8:9]
	s_add_u32 m0, s10, 0x4400
	s_nop 0
	global_load_lds_dwordx4 v131, s[8:9]
	s_add_u32 m0, s10, 0x4800
	s_nop 0
	global_load_lds_dwordx4 v132, s[8:9]
	s_add_u32 m0, s10, 0x4c00
	s_nop 0
	global_load_lds_dwordx4 v133, s[8:9]
	s_add_u32 s8, s8, 128
	s_addc_u32 s9, s9, 0
	s_movk_i32 s11, 16
	s_waitcnt vmcnt(0)
	s_barrier
	ds_read_b128 v[66:69], v134 offset:0
	ds_read_b128 v[70:73], v134 offset:2048
	ds_read_b128 v[74:77], v134 offset:4096
	ds_read_b128 v[78:81], v134 offset:6144
	ds_read_b128 v[82:85], v136 offset:0
	ds_read_b128 v[86:89], v136 offset:2048
	ds_read_b128 v[90:93], v136 offset:4096
	ds_read_b128 v[94:97], v136 offset:6144
	ds_read_b128 v[98:101], v135 offset:0
	ds_read_b128 v[102:105], v135 offset:2048
	ds_read_b128 v[106:109], v135 offset:4096
	ds_read_b128 v[110:113], v135 offset:6144
	ds_read_b128 v[114:117], v137 offset:0
	ds_read_b128 v[118:121], v137 offset:2048
	ds_read_b128 v[122:125], v137 offset:4096
	ds_read_b128 v[126:129], v137 offset:6144
.Lop16_loop:
	s_waitcnt lgkmcnt(8)
	s_add_u32 m0, s10, 0x8000
	v_mfma_f32_16x16x32_bf16 v[2:5], v[82:85], v[66:69], v[2:5]
	global_load_lds_dwordx4 v130, s[4:5]
	v_mfma_f32_16x16x32_bf16 v[6:9], v[86:89], v[66:69], v[6:9]
	s_add_u32 m0, s10, 0x8400
	v_mfma_f32_16x16x32_bf16 v[10:13], v[90:93], v[66:69], v[10:13]
	global_load_lds_dwordx4 v131, s[4:5]
	v_mfma_f32_16x16x32_bf16 v[14:17], v[94:97], v[66:69], v[14:17]
	s_add_u32 m0, s10, 0x8800
	v_mfma_f32_16x16x32_bf16 v[18:21], v[82:85], v[70:73], v[18:21]
	global_load_lds_dwordx4 v132, s[4:5]
	v_mfma_f32_16x16x32_bf16 v[22:25], v[86:89], v[70:73], v[22:25]
	s_add_u32 m0, s10, 0x8c00
	v_mfma_f32_16x16x32_bf16 v[26:29], v[90:93], v[70:73], v[26:29]
	global_load_lds_dwordx4 v133, s[4:5]
	s_add_u32 s4, s4, 128
	s_addc_u32 s5, s5, 0
	v_mfma_f32_16x16x32_bf16 v[30:33], v[94:97], v[70:73], v[30:33]
	s_add_u32 m0, s10, 0xc000
	v_mfma_f32_16x16x32_bf16 v[34:37], v[82:85], v[74:77], v[34:37]
	global_load_lds_dwordx4 v130, s[8:9]
	v_mfma_f32_16x16x32_bf16 v[38:41], v[86:89], v[74:77], v[38:41]
	s_add_u32 m0, s10, 0xc400
	v_mfma_f32_16x16x32_bf16 v[42:45], v[90:93], v[74:77], v[42:45]
	global_load_lds_dwordx4 v131, s[8:9]
	v_mfma_f32_16x16x32_bf16 v[46:49], v[94:97], v[74:77], v[46:49]
	s_add_u32 m0, s10, 0xc800
	v_mfma_f32_16x16x32_bf16 v[50:53], v[82:85], v[78:81], v[50:53]
	global_load_lds_dwordx4 v132, s[8:9]
	v_mfma_f32_16x16x32_bf16 v[54:57], v[86:89], v[78:81], v[54:57]
	s_add_u32 m0, s10, 0xcc00
	v_mfma_f32_16x16x32_bf16 v[58:61], v[90:93], v[78:81], v[58:61]
	global_load_lds_dwordx4 v133, s[8:9]
	s_add_u32 s8, s8, 128
	s_addc_u32 s9, s9, 0
	v_mfma_f32_16x16x32_bf16 v[62:65], v[94:97], v[78:81], v[62:65]
	s_waitcnt lgkmcnt(0)
	v_mfma_f32_16x16x32_bf16 v[2:5], v[114:117], v[98:101], v[2:5]
	v_mfma_f32_16x16x32_bf16 v[6:9], v[118:121], v[98:101], v[6:9]
	v_mfma_f32_16x16x32_bf16 v[10:13], v[122:125], v[98:101], v[10:13]
	v_mfma_f32_16x16x32_bf16 v[14:17], v[126:129], v[98:101], v[14:17]
	v_mfma_f32_16x16x32_bf16 v[18:21], v[114:117], v[102:105], v[18:21]
	v_mfma_f32_16x16x32_bf16 v[22:25], v[118:121], v[102:105], v[22:25]
	v_mfma_f32_16x16x32_bf16 v[26:29], v[122:125], v[102:105], v[26:29]
	v_mfma_f32_16x16x32_bf16 v[30:33], v[126:129], v[102:105], v[30:33]
	s_waitcnt vmcnt(0)
	s_barrier
; #define G_STORE(S, bf) { *(uint4*)&s->a[bf][srow][skc] = S##a0; *(uint4*)&s->a[bf][srow + 32][skc] = S##a1; \
;     if (MB == 2) { *(uint4*)&s->a[bf][srow + 64][skc] = S##a2; *(uint4*)&s->a[bf][srow + 96][skc] = S##a3; } \
;     *(uint4*)&s->b[bf][srow][skc] = S##b0; *(uint4*)&s->b[bf][srow + 32][skc] = S##b1; *(uint4*)&s->b[bf][srow + 64][skc] = S##b2; *(uint4*)&s->b[bf][srow + 96][skc] = S##b3; }
; template <int MB, bool PF2 = true>
; DI void gemm_main(const u16* __restrict__ A, int lda, const u16* __restrict__ B, int ldb, int K, f32x16 (&acc)[MB][2], GemmLds* s, int tid) {
;     ...
;   for (int kt = 0; kt < KT; kt += 2) {
;     { const int k2 = min((kt + 2) * 64, klast); G_LOAD(q, k2); }
;     __builtin_amdgcn_sched_barrier(0);
;     G_COMPUTE(0);
;     G_STORE(p, 1);
;     __syncthreads();
;     { const int k3 = min((kt + 3) * 64, klast); G_LOAD(p, k3); }
;     __builtin_amdgcn_sched_barrier(0);
;     G_COMPUTE(1);
;     G_STORE(q, 0);
;     __syncthreads();
;   }
	ds_read_b128 v[66:69], v134 offset:32768
	ds_read_b128 v[70:73], v134 offset:34816
	ds_read_b128 v[74:77], v134 offset:36864
	ds_read_b128 v[78:81], v134 offset:38912
	ds_read_b128 v[82:85], v136 offset:32768
	ds_read_b128 v[86:89], v136 offset:34816
	ds_read_b128 v[90:93], v136 offset:36864
	ds_read_b128 v[94:97], v136 offset:38912
	v_mfma_f32_16x16x32_bf16 v[34:37], v[114:117], v[106:109], v[34:37]
	v_mfma_f32_16x16x32_bf16 v[38:41], v[118:121], v[106:109], v[38:41]
	v_mfma_f32_16x16x32_bf16 v[42:45], v[122:125], v[106:109], v[42:45]
	v_mfma_f32_16x16x32_bf16 v[46:49], v[126:129], v[106:109], v[46:49]
	v_mfma_f32_16x16x32_bf16 v[50:53], v[114:117], v[110:113], v[50:53]
	v_mfma_f32_16x16x32_bf16 v[54:57], v[118:121], v[110:113], v[54:57]
	v_mfma_f32_16x16x32_bf16 v[58:61], v[122:125], v[110:113], v[58:61]
	v_mfma_f32_16x16x32_bf16 v[62:65], v[126:129], v[110:113], v[62:65]
	ds_read_b128 v[98:101], v135 offset:32768
	ds_read_b128 v[102:105], v135 offset:34816
	ds_read_b128 v[106:109], v135 offset:36864
	ds_read_b128 v[110:113], v135 offset:38912
	ds_read_b128 v[114:117], v137 offset:32768
	ds_read_b128 v[118:121], v137 offset:34816
	ds_read_b128 v[122:125], v137 offset:36864
	ds_read_b128 v[126:129], v137 offset:38912
	s_sub_u32 s11, s11, 2
	s_cmp_eq_u32 s11, 0
	s_cbranch_scc1 .Lop16_last
	s_waitcnt lgkmcnt(8)
	s_add_u32 m0, s10, 0x0
	v_mfma_f32_16x16x32_bf16 v[2:5], v[82:85], v[66:69], v[2:5]
	global_load_lds_dwordx4 v130, s[4:5]
	v_mfma_f32_16x16x32_bf16 v[6:9], v[86:89], v[66:69], v[6:9]
	s_add_u32 m0, s10, 0x400
	v_mfma_f32_16x16x32_bf16 v[10:13], v[90:93], v[66:69], v[10:13]
	global_load_lds_dwordx4 v131, s[4:5]
	v_mfma_f32_16x16x32_bf16 v[14:17], v[94:97], v[66:69], v[14:17]
	s_add_u32 m0, s10, 0x800
	v_mfma_f32_16x16x32_bf16 v[18:21], v[82:85], v[70:73], v[18:21]
	global_load_lds_dwordx4 v132, s[4:5]
	v_mfma_f32_16x16x32_bf16 v[22:25], v[86:89], v[70:73], v[22:25]
	s_add_u32 m0, s10, 0xc00
	v_mfma_f32_16x16x32_bf16 v[26:29], v[90:93], v[70:73], v[26:29]
	global_load_lds_dwordx4 v133, s[4:5]
	s_add_u32 s4, s4, 128
	s_addc_u32 s5, s5, 0
	v_mfma_f32_16x16x32_bf16 v[30:33], v[94:97], v[70:73], v[30:33]
	s_add_u32 m0, s10, 0x4000
	v_mfma_f32_16x16x32_bf16 v[34:37], v[82:85], v[74:77], v[34:37]
	global_load_lds_dwordx4 v130, s[8:9]
	v_mfma_f32_16x16x32_bf16 v[38:41], v[86:89], v[74:77], v[38:41]
	s_add_u32 m0, s10, 0x4400
	v_mfma_f32_16x16x32_bf16 v[42:45], v[90:93], v[74:77], v[42:45]
	global_load_lds_dwordx4 v131, s[8:9]
	v_mfma_f32_16x16x32_bf16 v[46:49], v[94:97], v[74:77], v[46:49]
	s_add_u32 m0, s10, 0x4800
	v_mfma_f32_16x16x32_bf16 v[50:53], v[82:85], v[78:81], v[50:53]
	global_load_lds_dwordx4 v132, s[8:9]
	v_mfma_f32_16x16x32_bf16 v[54:57], v[86:89], v[78:81], v[54:57]
	s_add_u32 m0, s10, 0x4c00
	v_mfma_f32_16x16x32_bf16 v[58:61], v[90:93], v[78:81], v[58:61]
	global_load_lds_dwordx4 v133, s[8:9]
	s_add_u32 s8, s8, 128
	s_addc_u32 s9, s9, 0
	v_mfma_f32_16x16x32_bf16 v[62:65], v[94:97], v[78:81], v[62:65]
	s_waitcnt lgkmcnt(0)
	v_mfma_f32_16x16x32_bf16 v[2:5], v[114:117], v[98:101], v[2:5]
	v_mfma_f32_16x16x32_bf16 v[6:9], v[118:121], v[98:101], v[6:9]
	v_mfma_f32_16x16x32_bf16 v[10:13], v[122:125], v[98:101], v[10:13]
	v_mfma_f32_16x16x32_bf16 v[14:17], v[126:129], v[98:101], v[14:17]
	v_mfma_f32_16x16x32_bf16 v[18:21], v[114:117], v[102:105], v[18:21]
	v_mfma_f32_16x16x32_bf16 v[22:25], v[118:121], v[102:105], v[22:25]
	v_mfma_f32_16x16x32_bf16 v[26:29], v[122:125], v[102:105], v[26:29]
	v_mfma_f32_16x16x32_bf16 v[30:33], v[126:129], v[102:105], v[30:33]
	s_waitcnt vmcnt(0)
	s_barrier
	ds_read_b128 v[66:69], v134 offset:0
	ds_read_b128 v[70:73], v134 offset:2048
	ds_read_b128 v[74:77], v134 offset:4096
	ds_read_b128 v[78:81], v134 offset:6144
	ds_read_b128 v[82:85], v136 offset:0
	ds_read_b128 v[86:89], v136 offset:2048
	ds_read_b128 v[90:93], v136 offset:4096
	ds_read_b128 v[94:97], v136 offset:6144
	v_mfma_f32_16x16x32_bf16 v[34:37], v[114:117], v[106:109], v[34:37]
	v_mfma_f32_16x16x32_bf16 v[38:41], v[118:121], v[106:109], v[38:41]
	v_mfma_f32_16x16x32_bf16 v[42:45], v[122:125], v[106:109], v[42:45]
	v_mfma_f32_16x16x32_bf16 v[46:49], v[126:129], v[106:109], v[46:49]
	v_mfma_f32_16x16x32_bf16 v[50:53], v[114:117], v[110:113], v[50:53]
	v_mfma_f32_16x16x32_bf16 v[54:57], v[118:121], v[110:113], v[54:57]
	v_mfma_f32_16x16x32_bf16 v[58:61], v[122:125], v[110:113], v[58:61]
	v_mfma_f32_16x16x32_bf16 v[62:65], v[126:129], v[110:113], v[62:65]
	ds_read_b128 v[98:101], v135 offset:0
	ds_read_b128 v[102:105], v135 offset:2048
	ds_read_b128 v[106:109], v135 offset:4096
	ds_read_b128 v[110:113], v135 offset:6144
	ds_read_b128 v[114:117], v137 offset:0
	ds_read_b128 v[118:121], v137 offset:2048
	ds_read_b128 v[122:125], v137 offset:4096
	ds_read_b128 v[126:129], v137 offset:6144
	s_branch .Lop16_loop
; #define G_STORE(S, bf) { *(uint4*)&s->a[bf][srow][skc] = S##a0; *(uint4*)&s->a[bf][srow + 32][skc] = S##a1; \
;     if (MB == 2) { *(uint4*)&s->a[bf][srow + 64][skc] = S##a2; *(uint4*)&s->a[bf][srow + 96][skc] = S##a3; } \
;     *(uint4*)&s->b[bf][srow][skc] = S##b0; *(uint4*)&s->b[bf][srow + 32][skc] = S##b1; *(uint4*)&s->b[bf][srow + 64][skc] = S##b2; *(uint4*)&s->b[bf][srow + 96][skc] = S##b3; }
; template <int MB, bool PF2 = true>
; DI void gemm_main(const u16* __restrict__ A, int lda, const u16* __restrict__ B, int ldb, int K, f32x16 (&acc)[MB][2], GemmLds* s, int tid) {
;     ...
;   for (int kt = 0; kt < KT; kt += 2) {
;     { const int k2 = min((kt + 2) * 64, klast); G_LOAD(q, k2); }
;     __builtin_amdgcn_sched_barrier(0);
;     G_COMPUTE(0);
;     G_STORE(p, 1);
;     __syncthreads();
;     { const int k3 = min((kt + 3) * 64, klast); G_LOAD(p, k3); }
;     __builtin_amdgcn_sched_barrier(0);
;     G_COMPUTE(1);
;     G_STORE(q, 0);
;     __syncthreads();
;   }
.Lop16_last:
	s_waitcnt lgkmcnt(8)
	v_mfma_f32_16x16x32_bf16 v[2:5], v[82:85], v[66:69], v[2:5]
	v_mfma_f32_16x16x32_bf16 v[6:9], v[86:89], v[66:69], v[6:9]
	v_mfma_f32_16x16x32_bf16 v[10:13], v[90:93], v[66:69], v[10:13]
	v_mfma_f32_16x16x32_bf16 v[14:17], v[94:97], v[66:69], v[14:17]
	v_mfma_f32_16x16x32_bf16 v[18:21], v[82:85], v[70:73], v[18:21]
	v_mfma_f32_16x16x32_bf16 v[22:25], v[86:89], v[70:73], v[22:25]
	v_mfma_f32_16x16x32_bf16 v[26:29], v[90:93], v[70:73], v[26:29]
	v_mfma_f32_16x16x32_bf16 v[30:33], v[94:97], v[70:73], v[30:33]
	v_mfma_f32_16x16x32_bf16 v[34:37], v[82:85], v[74:77], v[34:37]
	v_mfma_f32_16x16x32_bf16 v[38:41], v[86:89], v[74:77], v[38:41]
	v_mfma_f32_16x16x32_bf16 v[42:45], v[90:93], v[74:77], v[42:45]
	v_mfma_f32_16x16x32_bf16 v[46:49], v[94:97], v[74:77], v[46:49]
	v_mfma_f32_16x16x32_bf16 v[50:53], v[82:85], v[78:81], v[50:53]
	v_mfma_f32_16x16x32_bf16 v[54:57], v[86:89], v[78:81], v[54:57]
	v_mfma_f32_16x16x32_bf16 v[58:61], v[90:93], v[78:81], v[58:61]
	v_mfma_f32_16x16x32_bf16 v[62:65], v[94:97], v[78:81], v[62:65]
	s_waitcnt lgkmcnt(0)
	v_mfma_f32_16x16x32_bf16 v[2:5], v[114:117], v[98:101], v[2:5]
	v_mfma_f32_16x16x32_bf16 v[6:9], v[118:121], v[98:101], v[6:9]
	v_mfma_f32_16x16x32_bf16 v[10:13], v[122:125], v[98:101], v[10:13]
	v_mfma_f32_16x16x32_bf16 v[14:17], v[126:129], v[98:101], v[14:17]
	v_mfma_f32_16x16x32_bf16 v[18:21], v[114:117], v[102:105], v[18:21]
	v_mfma_f32_16x16x32_bf16 v[22:25], v[118:121], v[102:105], v[22:25]
	v_mfma_f32_16x16x32_bf16 v[26:29], v[122:125], v[102:105], v[26:29]
	v_mfma_f32_16x16x32_bf16 v[30:33], v[126:129], v[102:105], v[30:33]
	v_mfma_f32_16x16x32_bf16 v[34:37], v[114:117], v[106:109], v[34:37]
	v_mfma_f32_16x16x32_bf16 v[38:41], v[118:121], v[106:109], v[38:41]
	v_mfma_f32_16x16x32_bf16 v[42:45], v[122:125], v[106:109], v[42:45]
	v_mfma_f32_16x16x32_bf16 v[46:49], v[126:129], v[106:109], v[46:49]
	v_mfma_f32_16x16x32_bf16 v[50:53], v[114:117], v[110:113], v[50:53]
	v_mfma_f32_16x16x32_bf16 v[54:57], v[118:121], v[110:113], v[54:57]
	v_mfma_f32_16x16x32_bf16 v[58:61], v[122:125], v[110:113], v[58:61]
	v_mfma_f32_16x16x32_bf16 v[62:65], v[126:129], v[110:113], v[62:65]
	s_barrier
; DI u16 f2bf(float x) { return (u16)(pack2(x, 0.f) & 0xffffu); }
; DI int crow(int i, int h) { return (i & 3) + 8 * (i >> 2) + 4 * h; }
; DI void phase_outproj(const Params& p, int l, char* smem, int tid) {
;     ...
;     u16* O = p.G;
; #pragma unroll
;     for (int mb = 0; mb < 2; mb++)
; #pragma unroll
;       for (int nb = 0; nb < 2; nb++) {
;         const int rowb = m0 + wm * 64 + mb * 32, col = n0 + wn * 64 + nb * 32 + r;
;         const int b = rowb / SEQA, pos0 = rowb % SEQA;
;         const float gate = p.mod[((size_t)l * 9 + ((pos0 < CTXL) ? 8 : b)) * 3072 + 2048 + col];
; #pragma unroll
;         for (int i = 0; i < 16; i++) O[(size_t)(rowb + crow(i, h)) * 1024 + col] = f2bf(gate * acc[mb][nb][i]);
;       }
;   }
	s_nop 7
	s_nop 7
	v_mul_f32_e32 v2, v168, v2
	v_mul_f32_e32 v3, v169, v3
	v_mul_f32_e32 v4, v170, v4
	v_mul_f32_e32 v5, v171, v5
	v_mul_f32_e32 v6, v172, v6
	v_mul_f32_e32 v7, v173, v7
	v_mul_f32_e32 v8, v174, v8
	v_mul_f32_e32 v9, v175, v9
	v_mul_f32_e32 v10, v176, v10
	v_mul_f32_e32 v11, v177, v11
	v_mul_f32_e32 v12, v178, v12
	v_mul_f32_e32 v13, v179, v13
	v_mul_f32_e32 v14, v180, v14
	v_mul_f32_e32 v15, v181, v15
	v_mul_f32_e32 v16, v182, v16
	v_mul_f32_e32 v17, v183, v17
	v_mul_f32_e32 v18, v168, v18
	v_mul_f32_e32 v19, v169, v19
	v_mul_f32_e32 v20, v170, v20
	v_mul_f32_e32 v21, v171, v21
	v_mul_f32_e32 v22, v172, v22
	v_mul_f32_e32 v23, v173, v23
	v_mul_f32_e32 v24, v174, v24
	v_mul_f32_e32 v25, v175, v25
	v_mul_f32_e32 v26, v176, v26
	v_mul_f32_e32 v27, v177, v27
	v_mul_f32_e32 v28, v178, v28
	v_mul_f32_e32 v29, v179, v29
	v_mul_f32_e32 v30, v180, v30
	v_mul_f32_e32 v31, v181, v31
	v_mul_f32_e32 v32, v182, v32
	v_mul_f32_e32 v33, v183, v33
	v_mul_f32_e32 v34, v168, v34
	v_mul_f32_e32 v35, v169, v35
	v_mul_f32_e32 v36, v170, v36
	v_mul_f32_e32 v37, v171, v37
	v_mul_f32_e32 v38, v172, v38
	v_mul_f32_e32 v39, v173, v39
	v_mul_f32_e32 v40, v174, v40
	v_mul_f32_e32 v41, v175, v41
	v_mul_f32_e32 v42, v176, v42
	v_mul_f32_e32 v43, v177, v43
	v_mul_f32_e32 v44, v178, v44
	v_mul_f32_e32 v45, v179, v45
	v_mul_f32_e32 v46, v180, v46
	v_mul_f32_e32 v47, v181, v47
	v_mul_f32_e32 v48, v182, v48
	v_mul_f32_e32 v49, v183, v49
	v_mul_f32_e32 v50, v168, v50
	v_mul_f32_e32 v51, v169, v51
	v_mul_f32_e32 v52, v170, v52
	v_mul_f32_e32 v53, v171, v53
	v_mul_f32_e32 v54, v172, v54
	v_mul_f32_e32 v55, v173, v55
	v_mul_f32_e32 v56, v174, v56
	v_mul_f32_e32 v57, v175, v57
	v_mul_f32_e32 v58, v176, v58
	v_mul_f32_e32 v59, v177, v59
	v_mul_f32_e32 v60, v178, v60
	v_mul_f32_e32 v61, v179, v61
	v_mul_f32_e32 v62, v180, v62
	v_mul_f32_e32 v63, v181, v63
	v_mul_f32_e32 v64, v182, v64
	v_mul_f32_e32 v65, v183, v65
	v_cvt_pk_bf16_f32 v156, v2, v3
	v_cvt_pk_bf16_f32 v157, v4, v5
	ds_write_b64 v164, v[156:157] offset:0
	v_cvt_pk_bf16_f32 v158, v6, v7
	v_cvt_pk_bf16_f32 v159, v8, v9
	ds_write_b64 v164, v[158:159] offset:32
	v_cvt_pk_bf16_f32 v160, v10, v11
	v_cvt_pk_bf16_f32 v161, v12, v13
	ds_write_b64 v164, v[160:161] offset:64
	v_cvt_pk_bf16_f32 v162, v14, v15
	v_cvt_pk_bf16_f32 v163, v16, v17
	ds_write_b64 v164, v[162:163] offset:96
	v_cvt_pk_bf16_f32 v156, v18, v19
	v_cvt_pk_bf16_f32 v157, v20, v21
	ds_write_b64 v164, v[156:157] offset:2304
	v_cvt_pk_bf16_f32 v158, v22, v23
	v_cvt_pk_bf16_f32 v159, v24, v25
	ds_write_b64 v164, v[158:159] offset:2336
	v_cvt_pk_bf16_f32 v160, v26, v27
	v_cvt_pk_bf16_f32 v161, v28, v29
	ds_write_b64 v164, v[160:161] offset:2368
	v_cvt_pk_bf16_f32 v162, v30, v31
	v_cvt_pk_bf16_f32 v163, v32, v33
	ds_write_b64 v164, v[162:163] offset:2400
	v_cvt_pk_bf16_f32 v156, v34, v35
	v_cvt_pk_bf16_f32 v157, v36, v37
	ds_write_b64 v164, v[156:157] offset:4608
	v_cvt_pk_bf16_f32 v158, v38, v39
	v_cvt_pk_bf16_f32 v159, v40, v41
	ds_write_b64 v164, v[158:159] offset:4640
	v_cvt_pk_bf16_f32 v160, v42, v43
	v_cvt_pk_bf16_f32 v161, v44, v45
	ds_write_b64 v164, v[160:161] offset:4672
	v_cvt_pk_bf16_f32 v162, v46, v47
	v_cvt_pk_bf16_f32 v163, v48, v49
	ds_write_b64 v164, v[162:163] offset:4704
	v_cvt_pk_bf16_f32 v156, v50, v51
	v_cvt_pk_bf16_f32 v157, v52, v53
	ds_write_b64 v164, v[156:157] offset:6912
	v_cvt_pk_bf16_f32 v158, v54, v55
	v_cvt_pk_bf16_f32 v159, v56, v57
	ds_write_b64 v164, v[158:159] offset:6944
	v_cvt_pk_bf16_f32 v160, v58, v59
	v_cvt_pk_bf16_f32 v161, v60, v61
	ds_write_b64 v164, v[160:161] offset:6976
	v_cvt_pk_bf16_f32 v162, v62, v63
	v_cvt_pk_bf16_f32 v163, v64, v65
	ds_write_b64 v164, v[162:163] offset:7008
	ds_read_b128 v[66:69], v165 offset:0
	ds_read_b128 v[70:73], v165 offset:1152
	ds_read_b128 v[74:77], v165 offset:2304
	ds_read_b128 v[78:81], v165 offset:3456
	ds_read_b128 v[82:85], v165 offset:4608
	ds_read_b128 v[86:89], v165 offset:5760
	ds_read_b128 v[90:93], v165 offset:6912
	ds_read_b128 v[94:97], v165 offset:8064
	s_waitcnt lgkmcnt(7)
	global_store_dwordx4 v166, v[66:69], s[16:17]
	s_add_u32 s16, s16, 0x4000
	s_addc_u32 s17, s17, 0
	s_waitcnt lgkmcnt(6)
	global_store_dwordx4 v166, v[70:73], s[16:17]
	s_add_u32 s16, s16, 0x4000
	s_addc_u32 s17, s17, 0
	s_waitcnt lgkmcnt(5)
	global_store_dwordx4 v166, v[74:77], s[16:17]
	s_add_u32 s16, s16, 0x4000
	s_addc_u32 s17, s17, 0
	s_waitcnt lgkmcnt(4)
	global_store_dwordx4 v166, v[78:81], s[16:17]
	s_add_u32 s16, s16, 0x4000
	s_addc_u32 s17, s17, 0
	s_waitcnt lgkmcnt(3)
	global_store_dwordx4 v166, v[82:85], s[16:17]
	s_add_u32 s16, s16, 0x4000
	s_addc_u32 s17, s17, 0
	s_waitcnt lgkmcnt(2)
	global_store_dwordx4 v166, v[86:89], s[16:17]
	s_add_u32 s16, s16, 0x4000
	s_addc_u32 s17, s17, 0
	s_waitcnt lgkmcnt(1)
	global_store_dwordx4 v166, v[90:93], s[16:17]
	s_add_u32 s16, s16, 0x4000
	s_addc_u32 s17, s17, 0
	s_waitcnt lgkmcnt(0)
	global_store_dwordx4 v166, v[94:97], s[16:17]
	s_cmp_eq_u32 s18, 0
	s_cbranch_scc1 .Lop_item
	s_add_u32 s12, s12, s49
	s_branch .Lop_item
